# strategy 7.4: K-loop setprio flips deleted, one static s_setprio 1 for waves 0-3 at entry
# speedup vs baseline: 1.0064x; 1.0064x over previous
; #define LAS __attribute__((address_space(3)))
; __global__ void __launch_bounds__(NTHREADS, 2) hybrid_fwd(Params P) {
;     extern __shared__ __attribute__((aligned(16))) unsigned char lds_raw[];
;     LAS unsigned char* lds = (LAS unsigned char*)lds_raw;
;     cg::grid_group grid = cg::this_grid();
;     unsigned char* ws = P.ws;
;     volatile LAS unsigned* bst = (volatile LAS unsigned*)(lds + LDS_BYTES - 64);
;     if (threadIdx.x == 0) { bst[0] = 0u; bst[1] = 0u; }
;     __syncthreads();
;     XcdBarrier xbar = xcd_barrier_post((unsigned*)(ws + WS_BAR), bst);
_Z10hybrid_fwd6Params:
	s_load_dword s96, s[0:1], 0xa0
	s_load_dwordx4 s[88:91], s[0:1], 0x80
	s_load_dwordx2 s[84:85], s[0:1], 0x98
	s_mov_b32 s66, s2
	s_add_u32 s2, s0, 0x98
	v_and_b32_e32 v172, 0x3ff, v0
	s_addc_u32 s3, s1, 0
	v_cmp_eq_u32_e64 s[86:87], 0, v172
	s_nop 0
	v_readfirstlane_b32 s33, v172
	s_nop 3
	s_lshr_b32 s33, s33, 6
	s_cmp_lt_u32 s33, 4
	s_cbranch_scc0 .Lprio_done
	s_setprio 1
